# k50 plus: removed the compiler's s_waitcnt vmcnt(0) in front of the EP_RES and EP_SCALET K-loops (only LDS-DMA stages are in flight there; the template's counted waits cover them)
# speedup vs baseline: 1.0022x; 1.0009x over previous
.LBB0_276:
	s_add_u32 s3, s20, 0x100
	s_addc_u32 s34, s21, 0
	s_add_u32 s8, s30, 0x80
	v_mov_b64_e32 v[0:1], 0
	v_mov_b64_e32 v[2:3], 0
	v_mov_b64_e32 v[4:5], 0
	v_mov_b64_e32 v[6:7], 0
	v_mov_b64_e32 v[8:9], 0
	v_mov_b64_e32 v[10:11], 0
	v_mov_b64_e32 v[12:13], 0
	v_mov_b64_e32 v[14:15], 0
	v_mov_b64_e32 v[16:17], 0
	v_mov_b64_e32 v[18:19], 0
	v_mov_b64_e32 v[20:21], 0
	v_mov_b64_e32 v[22:23], 0
	v_mov_b64_e32 v[24:25], 0
	v_mov_b64_e32 v[26:27], 0
	v_mov_b64_e32 v[28:29], 0
	v_mov_b64_e32 v[30:31], 0
	v_mov_b64_e32 v[32:33], 0
	v_mov_b64_e32 v[34:35], 0
	v_mov_b64_e32 v[36:37], 0
	v_mov_b64_e32 v[38:39], 0
	v_mov_b64_e32 v[40:41], 0
	v_mov_b64_e32 v[42:43], 0
	v_mov_b64_e32 v[44:45], 0
	v_mov_b64_e32 v[46:47], 0
	v_mov_b64_e32 v[48:49], 0
	v_mov_b64_e32 v[50:51], 0
	v_mov_b64_e32 v[52:53], 0
	v_mov_b64_e32 v[54:55], 0
	v_mov_b64_e32 v[56:57], 0
	v_mov_b64_e32 v[58:59], 0
	v_mov_b64_e32 v[60:61], 0
	v_mov_b64_e32 v[62:63], 0
	v_mov_b64_e32 v[64:65], 0
	v_mov_b64_e32 v[66:67], 0
	v_mov_b64_e32 v[68:69], 0
	v_mov_b64_e32 v[70:71], 0
	v_mov_b64_e32 v[72:73], 0
	v_mov_b64_e32 v[74:75], 0
	v_mov_b64_e32 v[76:77], 0
	v_mov_b64_e32 v[78:79], 0
	v_mov_b64_e32 v[80:81], 0
	v_mov_b64_e32 v[82:83], 0
	v_mov_b64_e32 v[84:85], 0
	v_mov_b64_e32 v[86:87], 0
	v_mov_b64_e32 v[88:89], 0
	v_mov_b64_e32 v[90:91], 0
	v_mov_b64_e32 v[92:93], 0
	v_mov_b64_e32 v[94:95], 0
	v_mov_b64_e32 v[96:97], 0
	v_mov_b64_e32 v[98:99], 0
	v_mov_b64_e32 v[100:101], 0
	v_mov_b64_e32 v[102:103], 0
	v_mov_b64_e32 v[104:105], 0
	v_mov_b64_e32 v[106:107], 0
	v_mov_b64_e32 v[108:109], 0
	v_mov_b64_e32 v[110:111], 0
	v_mov_b64_e32 v[112:113], 0
	v_mov_b64_e32 v[114:115], 0
	v_mov_b64_e32 v[116:117], 0
	v_mov_b64_e32 v[118:119], 0
	v_mov_b64_e32 v[120:121], 0
	v_mov_b64_e32 v[122:123], 0
	v_mov_b64_e32 v[124:125], 0
	v_mov_b64_e32 v[126:127], 0
	s_addc_u32 s9, s31, 0
	s_mov_b32 s20, 0
	s_nop 0
	s_nop 0
	s_nop 0
	s_nop 0
	s_nop 0
	s_nop 0
	s_nop 0
	s_nop 0
	s_nop 0
	s_nop 0
	s_nop 0
	s_nop 0
	s_nop 0
	s_nop 0
	s_nop 0
	s_nop 0
	s_nop 0
	s_nop 0
	s_nop 0
	s_nop 0
	s_nop 0
	s_nop 0
	s_nop 0
	s_nop 0
	s_nop 0
	s_nop 0
	s_nop 0
	s_nop 0
	s_nop 0
	s_nop 0
	s_nop 0
	s_nop 0
	s_nop 0
	s_nop 0
	s_nop 0
	s_nop 0
	s_nop 0
	s_nop 0
	s_nop 0
	s_nop 0
	s_nop 0
	s_nop 0
